# code placement: one s_nop before the bf16-row GEMM K-loop head so that it sits at 0 mod 8 bytes like the baseline
# speedup vs baseline: 1.0046x; 1.0046x over previous
.Lmy_b16_pdefer:
	s_add_u32 s1, s12, 0xfffc0080
	s_addc_u32 s14, s13, -1
	s_add_i32 s33, 0, 0x10000
	s_cmp_eq_u32 s73, 12
	s_cselect_b32 s29, s11, s14
	s_cselect_b32 s28, s30, s1
	v_add_u32_e32 v100, s33, v154
	s_cselect_b32 s15, s31, s55
	s_cselect_b32 s14, s47, s54
	s_add_i32 s1, 0, 0x14000
	ds_read_b128 v[144:147], v100
	ds_read_b128 v[148:151], v100 offset:1024
	ds_read_b128 v[158:161], v100 offset:2048
	ds_read_b128 v[162:165], v100 offset:3072
	v_add_u32_e32 v100, s1, v154
	ds_read_b128 v[166:169], v100
	ds_read_b128 v[170:173], v100 offset:1024
	ds_read_b128 v[174:177], v100 offset:2048
	ds_read_b128 v[178:181], v100 offset:3072
	v_lshl_add_u64 v[152:153], s[12:13], 0, v[140:141]
	s_add_i32 m0, s41, 0xc000
	ds_read_b128 v[182:185], v156
	ds_read_b128 v[186:189], v156 offset:1024
	ds_read_b128 v[190:193], v156 offset:2048
	ds_read_b128 v[194:197], v156 offset:3072
	ds_read_b128 v[198:201], v156 offset:4096
	ds_read_b128 v[202:205], v156 offset:5120
	ds_read_b128 v[208:211], v156 offset:6144
	ds_read_b128 v[226:229], v156 offset:7168
	global_load_lds_dwordx4 v[152:153], off
	v_lshl_add_u64 v[152:153], s[12:13], 0, v[142:143]
	s_add_i32 m0, s41, 0xe000
	s_nop 0
	global_load_lds_dwordx4 v[152:153], off
	v_and_b32_e32 v100, 3, v224
	v_lshlrev_b32_e32 v100, 6, v100
	v_and_or_b32 v100, v224, 60, v100
	v_mov_b32_e32 v152, v247
	v_fmamk_f32 v234, v236, 0x3a800000, v207
	v_rsq_f32_e32 v234, v234
	s_nop 0
	v_mul_f32_e32 v234, s36, v234
	v_pk_mul_f32 v[126:127], v[126:127], v[234:235] op_sel_hi:[1,0]
	v_pk_mul_f32 v[128:129], v[128:129], v[234:235] op_sel_hi:[1,0]
	v_pk_mul_f32 v[122:123], v[122:123], v[234:235] op_sel_hi:[1,0]
	v_pk_mul_f32 v[124:125], v[124:125], v[234:235] op_sel_hi:[1,0]
	v_cvt_pk_bf16_f32 v126, v126, v127
	v_cvt_pk_bf16_f32 v127, v128, v129
	v_cvt_pk_bf16_f32 v128, v122, v123
	v_cvt_pk_bf16_f32 v129, v124, v125
	ds_bpermute_b32 v122, v100, v126
	ds_bpermute_b32 v123, v100, v127
	ds_bpermute_b32 v124, v100, v128
	ds_bpermute_b32 v125, v100, v129
	v_fmamk_f32 v234, v237, 0x3a800000, v207
	v_rsq_f32_e32 v234, v234
	s_nop 0
	v_mul_f32_e32 v234, s36, v234
	v_pk_mul_f32 v[110:111], v[110:111], v[234:235] op_sel_hi:[1,0]
	v_pk_mul_f32 v[112:113], v[112:113], v[234:235] op_sel_hi:[1,0]
	v_pk_mul_f32 v[106:107], v[106:107], v[234:235] op_sel_hi:[1,0]
	v_pk_mul_f32 v[108:109], v[108:109], v[234:235] op_sel_hi:[1,0]
	v_cvt_pk_bf16_f32 v110, v110, v111
	v_cvt_pk_bf16_f32 v111, v112, v113
	v_cvt_pk_bf16_f32 v112, v106, v107
	v_cvt_pk_bf16_f32 v113, v108, v109
	ds_bpermute_b32 v106, v100, v110
	ds_bpermute_b32 v107, v100, v111
	ds_bpermute_b32 v108, v100, v112
	ds_bpermute_b32 v109, v100, v113
	s_waitcnt lgkmcnt(4)
	global_store_dwordx4 v152, v[122:125], s[2:3] nt
	v_add_u32_e32 v152, s0, v152
	v_fmamk_f32 v234, v238, 0x3a800000, v207
	v_rsq_f32_e32 v234, v234
	s_nop 0
	v_mul_f32_e32 v234, s36, v234
	v_pk_mul_f32 v[92:93], v[92:93], v[234:235] op_sel_hi:[1,0]
	v_pk_mul_f32 v[94:95], v[94:95], v[234:235] op_sel_hi:[1,0]
	v_pk_mul_f32 v[88:89], v[88:89], v[234:235] op_sel_hi:[1,0]
	v_pk_mul_f32 v[90:91], v[90:91], v[234:235] op_sel_hi:[1,0]
	v_cvt_pk_bf16_f32 v92, v92, v93
	v_cvt_pk_bf16_f32 v93, v94, v95
	v_cvt_pk_bf16_f32 v94, v88, v89
	v_cvt_pk_bf16_f32 v95, v90, v91
	ds_bpermute_b32 v88, v100, v92
	ds_bpermute_b32 v89, v100, v93
	ds_bpermute_b32 v90, v100, v94
	ds_bpermute_b32 v91, v100, v95
	s_waitcnt lgkmcnt(4)
	global_store_dwordx4 v152, v[106:109], s[2:3] nt
	v_add_u32_e32 v152, s0, v152
	v_fmamk_f32 v234, v239, 0x3a800000, v207
	v_rsq_f32_e32 v234, v234
	s_nop 0
	v_mul_f32_e32 v234, s36, v234
	v_pk_mul_f32 v[76:77], v[76:77], v[234:235] op_sel_hi:[1,0]
	v_pk_mul_f32 v[78:79], v[78:79], v[234:235] op_sel_hi:[1,0]
	v_pk_mul_f32 v[72:73], v[72:73], v[234:235] op_sel_hi:[1,0]
	v_pk_mul_f32 v[74:75], v[74:75], v[234:235] op_sel_hi:[1,0]
	v_cvt_pk_bf16_f32 v76, v76, v77
	v_cvt_pk_bf16_f32 v77, v78, v79
	v_cvt_pk_bf16_f32 v78, v72, v73
	v_cvt_pk_bf16_f32 v79, v74, v75
	ds_bpermute_b32 v72, v100, v76
	ds_bpermute_b32 v73, v100, v77
	ds_bpermute_b32 v74, v100, v78
	ds_bpermute_b32 v75, v100, v79
	s_waitcnt lgkmcnt(4)
	global_store_dwordx4 v152, v[88:91], s[2:3] nt
	v_add_u32_e32 v152, s0, v152
	s_waitcnt lgkmcnt(0)
	global_store_dwordx4 v152, v[72:75], s[2:3] nt
	s_waitcnt vmcnt(12)
	s_waitcnt lgkmcnt(0)
	s_barrier
	s_setprio 1
	s_waitcnt lgkmcnt(0)
	v_mfma_f32_16x16x32_bf16 v[126:129], v[144:147], v[182:185], 0
	v_add_u32_e32 v153, s32, v247
	v_fmamk_f32 v230, v236, 0x3a800000, v207
	v_rsq_f32_e32 v230, v230
	s_nop 0
	v_mul_f32_e32 v230, s36, v230
	v_mfma_f32_16x16x32_bf16 v[122:125], v[158:161], v[182:185], 0
	v_mul_f32_e32 v118, v230, v118
	v_mul_f32_e32 v119, v230, v119
	v_mul_f32_e32 v120, v230, v120
	v_mul_f32_e32 v121, v230, v121
	v_mul_f32_e32 v114, v230, v114
	v_mul_f32_e32 v115, v230, v115
	v_mfma_f32_16x16x32_bf16 v[110:113], v[144:147], v[190:193], 0
	v_mul_f32_e32 v116, v230, v116
	v_mul_f32_e32 v117, v230, v117
	v_cvt_pk_bf16_f32 v118, v118, v119
	v_cvt_pk_bf16_f32 v119, v120, v121
	v_cvt_pk_bf16_f32 v120, v114, v115
	v_cvt_pk_bf16_f32 v121, v116, v117
	v_mfma_f32_16x16x32_bf16 v[106:109], v[158:161], v[190:193], 0
	ds_bpermute_b32 v114, v100, v118
	ds_bpermute_b32 v115, v100, v119
	ds_bpermute_b32 v116, v100, v120
	ds_bpermute_b32 v117, v100, v121
	v_fmamk_f32 v230, v237, 0x3a800000, v207
	v_rsq_f32_e32 v230, v230
	v_mfma_f32_16x16x32_bf16 v[92:95], v[144:147], v[198:201], 0
	s_nop 0
	v_mul_f32_e32 v230, s36, v230
	v_mul_f32_e32 v102, v230, v102
	v_mul_f32_e32 v103, v230, v103
	v_mul_f32_e32 v104, v230, v104
	v_mfma_f32_16x16x32_bf16 v[88:91], v[158:161], v[198:201], 0
	v_mul_f32_e32 v105, v230, v105
	v_mul_f32_e32 v96, v230, v96
	v_mul_f32_e32 v97, v230, v97
	v_mul_f32_e32 v98, v230, v98
	v_mul_f32_e32 v99, v230, v99
	v_cvt_pk_bf16_f32 v102, v102, v103
	v_mfma_f32_16x16x32_bf16 v[76:79], v[144:147], v[208:211], 0
	v_cvt_pk_bf16_f32 v103, v104, v105
	v_cvt_pk_bf16_f32 v104, v96, v97
	v_cvt_pk_bf16_f32 v105, v98, v99
	ds_bpermute_b32 v96, v100, v102
	ds_bpermute_b32 v97, v100, v103
	ds_bpermute_b32 v98, v100, v104
	v_mfma_f32_16x16x32_bf16 v[72:75], v[158:161], v[208:211], 0
	ds_bpermute_b32 v99, v100, v105
	s_waitcnt lgkmcnt(4)
	global_store_dwordx4 v153, v[114:117], s[2:3] nt
	v_add_u32_e32 v153, s0, v153
	v_fmamk_f32 v230, v238, 0x3a800000, v207
	v_rsq_f32_e32 v230, v230
	v_mfma_f32_16x16x32_bf16 v[126:129], v[148:151], v[186:189], v[126:129]
	s_nop 0
	v_mul_f32_e32 v230, s36, v230
	v_mul_f32_e32 v84, v230, v84
	v_mul_f32_e32 v85, v230, v85
	v_mul_f32_e32 v86, v230, v86
	v_mfma_f32_16x16x32_bf16 v[122:125], v[162:165], v[186:189], v[122:125]
	v_mul_f32_e32 v87, v230, v87
	v_mul_f32_e32 v80, v230, v80
	v_mul_f32_e32 v81, v230, v81
	v_mul_f32_e32 v82, v230, v82
	v_mul_f32_e32 v83, v230, v83
	v_cvt_pk_bf16_f32 v84, v84, v85
	v_mfma_f32_16x16x32_bf16 v[110:113], v[148:151], v[194:197], v[110:113]
	v_cvt_pk_bf16_f32 v85, v86, v87
	v_cvt_pk_bf16_f32 v86, v80, v81
	v_cvt_pk_bf16_f32 v87, v82, v83
	ds_bpermute_b32 v80, v100, v84
	ds_bpermute_b32 v81, v100, v85
	ds_bpermute_b32 v82, v100, v86
	v_mfma_f32_16x16x32_bf16 v[106:109], v[162:165], v[194:197], v[106:109]
	ds_bpermute_b32 v83, v100, v87
	s_waitcnt lgkmcnt(4)
	global_store_dwordx4 v153, v[96:99], s[2:3] nt
	v_add_u32_e32 v153, s0, v153
	v_fmamk_f32 v230, v239, 0x3a800000, v207
	v_rsq_f32_e32 v230, v230
	v_mfma_f32_16x16x32_bf16 v[92:95], v[148:151], v[202:205], v[92:95]
	s_nop 0
	v_mul_f32_e32 v230, s36, v230
	v_mul_f32_e32 v68, v230, v68
	v_mul_f32_e32 v69, v230, v69
	v_mul_f32_e32 v70, v230, v70
	v_mfma_f32_16x16x32_bf16 v[88:91], v[162:165], v[202:205], v[88:91]
	v_mul_f32_e32 v71, v230, v71
	v_mul_f32_e32 v64, v230, v64
	v_mul_f32_e32 v65, v230, v65
	v_mul_f32_e32 v66, v230, v66
	v_mul_f32_e32 v67, v230, v67
	v_cvt_pk_bf16_f32 v68, v68, v69
	v_mfma_f32_16x16x32_bf16 v[76:79], v[148:151], v[226:229], v[76:79]
	v_cvt_pk_bf16_f32 v69, v70, v71
	v_cvt_pk_bf16_f32 v70, v64, v65
	v_cvt_pk_bf16_f32 v71, v66, v67
	ds_bpermute_b32 v64, v100, v68
	ds_bpermute_b32 v65, v100, v69
	ds_bpermute_b32 v66, v100, v70
	v_mfma_f32_16x16x32_bf16 v[72:75], v[162:165], v[226:229], v[72:75]
	ds_bpermute_b32 v67, v100, v71
	s_waitcnt lgkmcnt(4)
	global_store_dwordx4 v153, v[80:83], s[2:3] nt
	v_add_u32_e32 v153, s0, v153
	s_waitcnt lgkmcnt(0)
	global_store_dwordx4 v153, v[64:67], s[2:3] nt
	s_setprio 0
	s_setprio 1
	v_mfma_f32_16x16x32_bf16 v[118:121], v[166:169], v[182:185], 0
	v_mov_b32_e32 v152, v247
	v_fmamk_f32 v234, v240, 0x3a800000, v207
	v_rsq_f32_e32 v234, v234
	s_nop 0
	v_mul_f32_e32 v234, s36, v234
	v_mfma_f32_16x16x32_bf16 v[114:117], v[174:177], v[182:185], 0
	v_mul_f32_e32 v60, v234, v60
	v_mul_f32_e32 v61, v234, v61
	v_mul_f32_e32 v62, v234, v62
	v_mul_f32_e32 v63, v234, v63
	v_mul_f32_e32 v56, v234, v56
	v_mul_f32_e32 v57, v234, v57
	v_mfma_f32_16x16x32_bf16 v[102:105], v[166:169], v[190:193], 0
	v_mul_f32_e32 v58, v234, v58
	v_mul_f32_e32 v59, v234, v59
	v_cvt_pk_bf16_f32 v60, v60, v61
	v_cvt_pk_bf16_f32 v61, v62, v63
	v_cvt_pk_bf16_f32 v62, v56, v57
	v_cvt_pk_bf16_f32 v63, v58, v59
	v_mfma_f32_16x16x32_bf16 v[96:99], v[174:177], v[190:193], 0
	ds_bpermute_b32 v56, v100, v60
	ds_bpermute_b32 v57, v100, v61
	ds_bpermute_b32 v58, v100, v62
	ds_bpermute_b32 v59, v100, v63
	v_fmamk_f32 v234, v244, 0x3a800000, v207
	v_rsq_f32_e32 v234, v234
	v_mfma_f32_16x16x32_bf16 v[84:87], v[166:169], v[198:201], 0
	s_nop 0
	v_mul_f32_e32 v234, s36, v234
	v_mul_f32_e32 v44, v234, v44
	v_mul_f32_e32 v45, v234, v45
	v_mul_f32_e32 v46, v234, v46
	v_mfma_f32_16x16x32_bf16 v[80:83], v[174:177], v[198:201], 0
	v_mul_f32_e32 v47, v234, v47
	v_mul_f32_e32 v40, v234, v40
	v_mul_f32_e32 v41, v234, v41
	v_mul_f32_e32 v42, v234, v42
	v_mul_f32_e32 v43, v234, v43
	v_cvt_pk_bf16_f32 v44, v44, v45
	v_mfma_f32_16x16x32_bf16 v[68:71], v[166:169], v[208:211], 0
	v_cvt_pk_bf16_f32 v45, v46, v47
	v_cvt_pk_bf16_f32 v46, v40, v41
	v_cvt_pk_bf16_f32 v47, v42, v43
	ds_bpermute_b32 v40, v100, v44
	ds_bpermute_b32 v41, v100, v45
	ds_bpermute_b32 v42, v100, v46
	v_mfma_f32_16x16x32_bf16 v[64:67], v[174:177], v[208:211], 0
	ds_bpermute_b32 v43, v100, v47
	s_waitcnt lgkmcnt(4)
	global_store_dwordx4 v152, v[56:59], s[90:91] nt
	v_add_u32_e32 v152, s0, v152
	v_fmamk_f32 v234, v245, 0x3a800000, v207
	v_rsq_f32_e32 v234, v234
	v_mfma_f32_16x16x32_bf16 v[118:121], v[170:173], v[186:189], v[118:121]
	s_nop 0
	v_mul_f32_e32 v234, s36, v234
	v_mul_f32_e32 v28, v234, v28
	v_mul_f32_e32 v29, v234, v29
	v_mul_f32_e32 v30, v234, v30
	v_mfma_f32_16x16x32_bf16 v[114:117], v[178:181], v[186:189], v[114:117]
	v_mul_f32_e32 v31, v234, v31
	v_mul_f32_e32 v24, v234, v24
	v_mul_f32_e32 v25, v234, v25
	v_mul_f32_e32 v26, v234, v26
	v_mul_f32_e32 v27, v234, v27
	v_cvt_pk_bf16_f32 v28, v28, v29
	v_mfma_f32_16x16x32_bf16 v[102:105], v[170:173], v[194:197], v[102:105]
	v_cvt_pk_bf16_f32 v29, v30, v31
	v_cvt_pk_bf16_f32 v30, v24, v25
	v_cvt_pk_bf16_f32 v31, v26, v27
	ds_bpermute_b32 v24, v100, v28
	ds_bpermute_b32 v25, v100, v29
	ds_bpermute_b32 v26, v100, v30
	v_mfma_f32_16x16x32_bf16 v[96:99], v[178:181], v[194:197], v[96:99]
	ds_bpermute_b32 v27, v100, v31
	s_waitcnt lgkmcnt(4)
	global_store_dwordx4 v152, v[40:43], s[90:91] nt
	v_add_u32_e32 v152, s0, v152
	v_fmamk_f32 v234, v246, 0x3a800000, v207
	v_rsq_f32_e32 v234, v234
	v_mfma_f32_16x16x32_bf16 v[84:87], v[170:173], v[202:205], v[84:87]
	s_nop 0
	v_mul_f32_e32 v234, s36, v234
	v_mul_f32_e32 v12, v234, v12
	v_mul_f32_e32 v13, v234, v13
	v_mul_f32_e32 v14, v234, v14
	v_mfma_f32_16x16x32_bf16 v[80:83], v[178:181], v[202:205], v[80:83]
	v_mul_f32_e32 v15, v234, v15
	v_mul_f32_e32 v8, v234, v8
	v_mul_f32_e32 v9, v234, v9
	v_mul_f32_e32 v10, v234, v10
	v_mul_f32_e32 v11, v234, v11
	v_cvt_pk_bf16_f32 v12, v12, v13
	v_mfma_f32_16x16x32_bf16 v[68:71], v[170:173], v[226:229], v[68:71]
	v_cvt_pk_bf16_f32 v13, v14, v15
	v_cvt_pk_bf16_f32 v14, v8, v9
	v_cvt_pk_bf16_f32 v15, v10, v11
	ds_bpermute_b32 v8, v100, v12
	ds_bpermute_b32 v9, v100, v13
	ds_bpermute_b32 v10, v100, v14
	v_mfma_f32_16x16x32_bf16 v[64:67], v[178:181], v[226:229], v[64:67]
	ds_bpermute_b32 v11, v100, v15
	s_waitcnt lgkmcnt(4)
	global_store_dwordx4 v152, v[24:27], s[90:91] nt
	v_add_u32_e32 v152, s0, v152
	s_waitcnt lgkmcnt(0)
	global_store_dwordx4 v152, v[8:11], s[90:91] nt
	s_setprio 0
	s_barrier
	s_add_i32 s33, s33, s34
	v_lshl_add_u64 v[152:153], s[14:15], 0, v[132:133]
	s_mov_b32 m0, s33
	ds_read_b128 v[182:185], v156 offset:16384
	ds_read_b128 v[186:189], v156 offset:17408
	ds_read_b128 v[190:193], v156 offset:18432
	ds_read_b128 v[194:197], v156 offset:19456
	ds_read_b128 v[198:201], v156 offset:20480
	ds_read_b128 v[202:205], v156 offset:21504
	ds_read_b128 v[208:211], v156 offset:22528
	ds_read_b128 v[226:229], v156 offset:23552
	global_load_lds_dwordx4 v[152:153], off
	s_add_i32 m0, s33, 0x2000
	s_add_u32 s80, s14, 0x40000
	v_lshl_add_u64 v[212:213], s[14:15], 0, v[136:137]
	s_addc_u32 s81, s15, 0
	s_add_i32 s1, s1, s34
	global_load_lds_dwordx4 v[212:213], off
	v_lshl_add_u64 v[230:231], s[80:81], 0, v[132:133]
	s_mov_b32 m0, s1
	v_lshl_add_u64 v[232:233], s[28:29], 0, v[134:135]
	global_load_lds_dwordx4 v[230:231], off
	v_lshl_add_u64 v[230:231], s[80:81], 0, v[136:137]
	s_add_i32 m0, s1, 0x2000
	s_nop 0
	global_load_lds_dwordx4 v[230:231], off
	v_lshl_add_u64 v[230:231], s[28:29], 0, v[130:131]
	s_mov_b32 m0, s41
	s_nop 0
	global_load_lds_dwordx4 v[230:231], off
	s_mov_b32 m0, s60
	s_nop 0
	global_load_lds_dwordx4 v[232:233], off
	s_waitcnt vmcnt(20)
	s_waitcnt lgkmcnt(0)
	s_barrier
	s_setprio 1
	s_waitcnt lgkmcnt(0)
	v_mfma_f32_16x16x32_bf16 v[60:63], v[144:147], v[182:185], 0
	v_and_b32_e32 v100, 3, v224
	v_lshlrev_b32_e32 v100, 6, v100
	v_and_or_b32 v100, v224, 60, v100
	v_add_u32_e32 v236, s32, v247
	v_fmamk_f32 v234, v240, 0x3a800000, v207
	v_mfma_f32_16x16x32_bf16 v[56:59], v[158:161], v[182:185], 0
	v_rsq_f32_e32 v234, v234
	s_nop 0
	v_mul_f32_e32 v234, s36, v234
	v_mul_f32_e32 v52, v234, v52
	v_mul_f32_e32 v53, v234, v53
	v_mul_f32_e32 v54, v234, v54
	v_mfma_f32_16x16x32_bf16 v[44:47], v[144:147], v[190:193], 0
	v_mul_f32_e32 v55, v234, v55
	v_mul_f32_e32 v48, v234, v48
	v_mul_f32_e32 v49, v234, v49
	v_mul_f32_e32 v50, v234, v50
	v_mul_f32_e32 v51, v234, v51
	v_cvt_pk_bf16_f32 v52, v52, v53
	v_mfma_f32_16x16x32_bf16 v[40:43], v[158:161], v[190:193], 0
	v_cvt_pk_bf16_f32 v53, v54, v55
	v_cvt_pk_bf16_f32 v54, v48, v49
	v_cvt_pk_bf16_f32 v55, v50, v51
	ds_bpermute_b32 v48, v100, v52
	ds_bpermute_b32 v49, v100, v53
	ds_bpermute_b32 v50, v100, v54
	v_mfma_f32_16x16x32_bf16 v[28:31], v[144:147], v[198:201], 0
	ds_bpermute_b32 v51, v100, v55
	v_fmamk_f32 v234, v244, 0x3a800000, v207
	v_rsq_f32_e32 v234, v234
	s_nop 0
	v_mul_f32_e32 v234, s36, v234
	v_mul_f32_e32 v36, v234, v36
	v_mfma_f32_16x16x32_bf16 v[24:27], v[158:161], v[198:201], 0
	v_mul_f32_e32 v37, v234, v37
	v_mul_f32_e32 v38, v234, v38
	v_mul_f32_e32 v39, v234, v39
	v_mul_f32_e32 v32, v234, v32
	v_mul_f32_e32 v33, v234, v33
	v_mul_f32_e32 v34, v234, v34
	v_mfma_f32_16x16x32_bf16 v[12:15], v[144:147], v[208:211], 0
	v_mul_f32_e32 v35, v234, v35
	v_cvt_pk_bf16_f32 v36, v36, v37
	v_cvt_pk_bf16_f32 v37, v38, v39
	v_cvt_pk_bf16_f32 v38, v32, v33
	v_cvt_pk_bf16_f32 v39, v34, v35
	ds_bpermute_b32 v32, v100, v36
	v_mfma_f32_16x16x32_bf16 v[8:11], v[158:161], v[208:211], 0
	ds_bpermute_b32 v33, v100, v37
	ds_bpermute_b32 v34, v100, v38
	ds_bpermute_b32 v35, v100, v39
	s_waitcnt lgkmcnt(4)
	global_store_dwordx4 v236, v[48:51], s[90:91] nt
	v_add_u32_e32 v236, s0, v236
	v_mfma_f32_16x16x32_bf16 v[60:63], v[148:151], v[186:189], v[60:63]
	v_fmamk_f32 v234, v245, 0x3a800000, v207
	v_rsq_f32_e32 v234, v234
	s_nop 0
	v_mul_f32_e32 v234, s36, v234
	v_mul_f32_e32 v20, v234, v20
	v_mul_f32_e32 v21, v234, v21
	v_mfma_f32_16x16x32_bf16 v[56:59], v[162:165], v[186:189], v[56:59]
	v_mul_f32_e32 v22, v234, v22
	v_mul_f32_e32 v23, v234, v23
	v_mul_f32_e32 v16, v234, v16
	v_mul_f32_e32 v17, v234, v17
	v_mul_f32_e32 v18, v234, v18
	v_mul_f32_e32 v19, v234, v19
	v_mfma_f32_16x16x32_bf16 v[44:47], v[148:151], v[194:197], v[44:47]
	v_cvt_pk_bf16_f32 v20, v20, v21
	v_cvt_pk_bf16_f32 v21, v22, v23
	v_cvt_pk_bf16_f32 v22, v16, v17
	v_cvt_pk_bf16_f32 v23, v18, v19
	ds_bpermute_b32 v16, v100, v20
	ds_bpermute_b32 v17, v100, v21
	v_mfma_f32_16x16x32_bf16 v[40:43], v[162:165], v[194:197], v[40:43]
	ds_bpermute_b32 v18, v100, v22
	ds_bpermute_b32 v19, v100, v23
	s_waitcnt lgkmcnt(4)
	global_store_dwordx4 v236, v[32:35], s[90:91] nt
	v_add_u32_e32 v236, s0, v236
	v_fmamk_f32 v234, v246, 0x3a800000, v207
	v_mfma_f32_16x16x32_bf16 v[28:31], v[148:151], v[202:205], v[28:31]
	v_rsq_f32_e32 v234, v234
	s_nop 0
	v_mul_f32_e32 v234, s36, v234
	v_mul_f32_e32 v4, v234, v4
	v_mul_f32_e32 v5, v234, v5
	v_mul_f32_e32 v6, v234, v6
	v_mfma_f32_16x16x32_bf16 v[24:27], v[162:165], v[202:205], v[24:27]
	v_mul_f32_e32 v7, v234, v7
	v_mul_f32_e32 v0, v234, v0
	v_mul_f32_e32 v1, v234, v1
	v_mul_f32_e32 v2, v234, v2
	v_mul_f32_e32 v3, v234, v3
	v_cvt_pk_bf16_f32 v4, v4, v5
	v_mfma_f32_16x16x32_bf16 v[12:15], v[148:151], v[226:229], v[12:15]
	v_cvt_pk_bf16_f32 v5, v6, v7
	v_cvt_pk_bf16_f32 v6, v0, v1
	v_cvt_pk_bf16_f32 v7, v2, v3
	ds_bpermute_b32 v0, v100, v4
	ds_bpermute_b32 v1, v100, v5
	ds_bpermute_b32 v2, v100, v6
	v_mfma_f32_16x16x32_bf16 v[8:11], v[162:165], v[226:229], v[8:11]
	ds_bpermute_b32 v3, v100, v7
	s_waitcnt lgkmcnt(4)
	global_store_dwordx4 v236, v[16:19], s[90:91] nt
	v_add_u32_e32 v236, s0, v236
	s_waitcnt lgkmcnt(0)
	global_store_dwordx4 v236, v[0:3], s[90:91] nt
	s_setprio 0
	s_setprio 1
	v_mfma_f32_16x16x32_bf16 v[52:55], v[166:169], v[182:185], 0
	v_mfma_f32_16x16x32_bf16 v[48:51], v[174:177], v[182:185], 0
	v_mfma_f32_16x16x32_bf16 v[36:39], v[166:169], v[190:193], 0
	v_mfma_f32_16x16x32_bf16 v[32:35], v[174:177], v[190:193], 0
	v_mfma_f32_16x16x32_bf16 v[20:23], v[166:169], v[198:201], 0
	v_mfma_f32_16x16x32_bf16 v[16:19], v[174:177], v[198:201], 0
	v_mfma_f32_16x16x32_bf16 v[4:7], v[166:169], v[208:211], 0
	v_mfma_f32_16x16x32_bf16 v[0:3], v[174:177], v[208:211], 0
	v_mfma_f32_16x16x32_bf16 v[52:55], v[170:173], v[186:189], v[52:55]
	v_mfma_f32_16x16x32_bf16 v[48:51], v[178:181], v[186:189], v[48:51]
	v_mfma_f32_16x16x32_bf16 v[36:39], v[170:173], v[194:197], v[36:39]
	v_mfma_f32_16x16x32_bf16 v[32:35], v[178:181], v[194:197], v[32:35]
	v_mfma_f32_16x16x32_bf16 v[20:23], v[170:173], v[202:205], v[20:23]
	v_mfma_f32_16x16x32_bf16 v[16:19], v[178:181], v[202:205], v[16:19]
	v_mfma_f32_16x16x32_bf16 v[4:7], v[170:173], v[226:229], v[4:7]
	v_mfma_f32_16x16x32_bf16 v[0:3], v[178:181], v[226:229], v[0:3]
	s_setprio 0
	s_barrier
	s_add_i32 s1, 0, 0x18000
	v_add_u32_e32 v100, s1, v154
	s_add_i32 s33, 0, 0x1c000
	ds_read_b128 v[144:147], v100
	ds_read_b128 v[148:151], v100 offset:1024
	ds_read_b128 v[158:161], v100 offset:2048
	ds_read_b128 v[162:165], v100 offset:3072
	v_add_u32_e32 v100, s33, v154
	ds_read_b128 v[166:169], v100
	ds_read_b128 v[170:173], v100 offset:1024
	ds_read_b128 v[174:177], v100 offset:2048
	ds_read_b128 v[178:181], v100 offset:3072
	s_add_u32 s28, s28, 0x40000
	s_addc_u32 s29, s29, 0
	s_mov_b32 m0, s61
	v_lshl_add_u64 v[234:235], s[28:29], 0, v[130:131]
	ds_read_b128 v[182:185], v156 offset:32768
	ds_read_b128 v[186:189], v156 offset:33792
	ds_read_b128 v[190:193], v156 offset:34816
	ds_read_b128 v[194:197], v156 offset:35840
	ds_read_b128 v[198:201], v156 offset:36864
	ds_read_b128 v[202:205], v156 offset:37888
	ds_read_b128 v[208:211], v156 offset:38912
	ds_read_b128 v[226:229], v156 offset:39936
	global_load_lds_dwordx4 v[234:235], off
	v_lshl_add_u64 v[234:235], s[28:29], 0, v[134:135]
	s_mov_b32 m0, s69
	s_nop 0
	global_load_lds_dwordx4 v[234:235], off
	s_lshl_b32 s46, s40, 8
	s_add_i32 s46, s46, s84
	v_or_b32_e32 v100, s46, v139
	v_lshlrev_b32_e32 v100, 2, v100
	global_load_dword v236, v100, s[66:67]
	global_load_dword v237, v100, s[66:67] offset:64
	global_load_dword v238, v100, s[66:67] offset:128
	global_load_dword v239, v100, s[66:67] offset:192
	global_load_dword v240, v100, s[66:67] offset:512
	global_load_dword v244, v100, s[66:67] offset:576
	global_load_dword v245, v100, s[66:67] offset:640
	global_load_dword v246, v100, s[66:67] offset:704
	s_waitcnt vmcnt(32)
	s_waitcnt lgkmcnt(0)
	s_barrier
	s_setprio 1
	s_waitcnt lgkmcnt(0)
	v_mfma_f32_16x16x32_bf16 v[126:129], v[144:147], v[182:185], v[126:129]
	v_mfma_f32_16x16x32_bf16 v[122:125], v[158:161], v[182:185], v[122:125]
	v_mfma_f32_16x16x32_bf16 v[110:113], v[144:147], v[190:193], v[110:113]
	v_mfma_f32_16x16x32_bf16 v[106:109], v[158:161], v[190:193], v[106:109]
	v_mfma_f32_16x16x32_bf16 v[92:95], v[144:147], v[198:201], v[92:95]
	v_mfma_f32_16x16x32_bf16 v[88:91], v[158:161], v[198:201], v[88:91]
	v_mfma_f32_16x16x32_bf16 v[76:79], v[144:147], v[208:211], v[76:79]
	v_mfma_f32_16x16x32_bf16 v[72:75], v[158:161], v[208:211], v[72:75]
	v_mfma_f32_16x16x32_bf16 v[126:129], v[148:151], v[186:189], v[126:129]
	v_mfma_f32_16x16x32_bf16 v[122:125], v[162:165], v[186:189], v[122:125]
	v_mfma_f32_16x16x32_bf16 v[110:113], v[148:151], v[194:197], v[110:113]
	v_mfma_f32_16x16x32_bf16 v[106:109], v[162:165], v[194:197], v[106:109]
	v_mfma_f32_16x16x32_bf16 v[92:95], v[148:151], v[202:205], v[92:95]
	v_mfma_f32_16x16x32_bf16 v[88:91], v[162:165], v[202:205], v[88:91]
	v_mfma_f32_16x16x32_bf16 v[76:79], v[148:151], v[226:229], v[76:79]
	v_mfma_f32_16x16x32_bf16 v[72:75], v[162:165], v[226:229], v[72:75]
	s_setprio 0
	s_setprio 1
	v_mfma_f32_16x16x32_bf16 v[118:121], v[166:169], v[182:185], v[118:121]
	v_mfma_f32_16x16x32_bf16 v[114:117], v[174:177], v[182:185], v[114:117]
	v_mfma_f32_16x16x32_bf16 v[102:105], v[166:169], v[190:193], v[102:105]
	v_mfma_f32_16x16x32_bf16 v[96:99], v[174:177], v[190:193], v[96:99]
	v_mfma_f32_16x16x32_bf16 v[84:87], v[166:169], v[198:201], v[84:87]
	v_mfma_f32_16x16x32_bf16 v[80:83], v[174:177], v[198:201], v[80:83]
	v_mfma_f32_16x16x32_bf16 v[68:71], v[166:169], v[208:211], v[68:71]
	v_mfma_f32_16x16x32_bf16 v[64:67], v[174:177], v[208:211], v[64:67]
	v_mfma_f32_16x16x32_bf16 v[118:121], v[170:173], v[186:189], v[118:121]
	v_mfma_f32_16x16x32_bf16 v[114:117], v[178:181], v[186:189], v[114:117]
	v_mfma_f32_16x16x32_bf16 v[102:105], v[170:173], v[194:197], v[102:105]
	v_mfma_f32_16x16x32_bf16 v[96:99], v[178:181], v[194:197], v[96:99]
	v_mfma_f32_16x16x32_bf16 v[84:87], v[170:173], v[202:205], v[84:87]
	v_mfma_f32_16x16x32_bf16 v[80:83], v[178:181], v[202:205], v[80:83]
	v_mfma_f32_16x16x32_bf16 v[68:71], v[170:173], v[226:229], v[68:71]
	v_mfma_f32_16x16x32_bf16 v[64:67], v[178:181], v[226:229], v[64:67]
	s_setprio 0
	s_barrier
	s_add_i32 s1, s1, s34
	v_lshl_add_u64 v[152:153], v[152:153], 0, s[86:87]
	s_mov_b32 m0, s1
	ds_read_b128 v[182:185], v156 offset:49152
	ds_read_b128 v[186:189], v156 offset:50176
	ds_read_b128 v[190:193], v156 offset:51200
	ds_read_b128 v[194:197], v156 offset:52224
	ds_read_b128 v[198:201], v156 offset:53248
	ds_read_b128 v[202:205], v156 offset:54272
	ds_read_b128 v[208:211], v156 offset:55296
	ds_read_b128 v[226:229], v156 offset:56320
	global_load_lds_dwordx4 v[152:153], off
	s_add_i32 m0, s1, 0x2000
	s_add_u32 s14, s14, 0x40080
	v_lshl_add_u64 v[152:153], v[212:213], 0, s[86:87]
	s_addc_u32 s15, s15, 0
	s_add_i32 s1, s33, s34
	global_load_lds_dwordx4 v[152:153], off
	v_lshl_add_u64 v[152:153], s[14:15], 0, v[132:133]
	s_mov_b32 m0, s1
	s_nop 0
	global_load_lds_dwordx4 v[152:153], off
	v_lshl_add_u64 v[152:153], s[14:15], 0, v[136:137]
	s_add_i32 m0, s1, 0x2000
	s_nop 0
	global_load_lds_dwordx4 v[152:153], off
	v_lshl_add_u64 v[152:153], v[230:231], 0, s[86:87]
	s_mov_b32 m0, s89
	s_nop 0
	global_load_lds_dwordx4 v[152:153], off
	v_lshl_add_u64 v[152:153], v[232:233], 0, s[86:87]
	s_mov_b32 m0, s92
	s_nop 0
	global_load_lds_dwordx4 v[152:153], off
	s_waitcnt vmcnt(20)
	s_waitcnt lgkmcnt(0)
	s_barrier
	s_setprio 1
	s_waitcnt lgkmcnt(0)
	v_mfma_f32_16x16x32_bf16 v[60:63], v[144:147], v[182:185], v[60:63]
	v_mfma_f32_16x16x32_bf16 v[56:59], v[158:161], v[182:185], v[56:59]
	v_mfma_f32_16x16x32_bf16 v[44:47], v[144:147], v[190:193], v[44:47]
	v_mfma_f32_16x16x32_bf16 v[40:43], v[158:161], v[190:193], v[40:43]
	v_mfma_f32_16x16x32_bf16 v[28:31], v[144:147], v[198:201], v[28:31]
	v_mfma_f32_16x16x32_bf16 v[24:27], v[158:161], v[198:201], v[24:27]
	v_mfma_f32_16x16x32_bf16 v[12:15], v[144:147], v[208:211], v[12:15]
	v_mfma_f32_16x16x32_bf16 v[8:11], v[158:161], v[208:211], v[8:11]
	v_mfma_f32_16x16x32_bf16 v[60:63], v[148:151], v[186:189], v[60:63]
	v_mfma_f32_16x16x32_bf16 v[56:59], v[162:165], v[186:189], v[56:59]
	v_mfma_f32_16x16x32_bf16 v[44:47], v[148:151], v[194:197], v[44:47]
	v_mfma_f32_16x16x32_bf16 v[40:43], v[162:165], v[194:197], v[40:43]
	v_mfma_f32_16x16x32_bf16 v[28:31], v[148:151], v[202:205], v[28:31]
	v_mfma_f32_16x16x32_bf16 v[24:27], v[162:165], v[202:205], v[24:27]
	v_mfma_f32_16x16x32_bf16 v[12:15], v[148:151], v[226:229], v[12:15]
	v_mfma_f32_16x16x32_bf16 v[8:11], v[162:165], v[226:229], v[8:11]
	s_setprio 0
	s_setprio 1
	v_mfma_f32_16x16x32_bf16 v[52:55], v[166:169], v[182:185], v[52:55]
	v_mfma_f32_16x16x32_bf16 v[48:51], v[174:177], v[182:185], v[48:51]
	v_mfma_f32_16x16x32_bf16 v[36:39], v[166:169], v[190:193], v[36:39]
	v_mfma_f32_16x16x32_bf16 v[32:35], v[174:177], v[190:193], v[32:35]
	v_mfma_f32_16x16x32_bf16 v[20:23], v[166:169], v[198:201], v[20:23]
	v_mfma_f32_16x16x32_bf16 v[16:19], v[174:177], v[198:201], v[16:19]
	v_mfma_f32_16x16x32_bf16 v[4:7], v[166:169], v[208:211], v[4:7]
	v_mfma_f32_16x16x32_bf16 v[0:3], v[174:177], v[208:211], v[0:3]
	v_mfma_f32_16x16x32_bf16 v[52:55], v[170:173], v[186:189], v[52:55]
	v_mfma_f32_16x16x32_bf16 v[48:51], v[178:181], v[186:189], v[48:51]
	v_mfma_f32_16x16x32_bf16 v[36:39], v[170:173], v[194:197], v[36:39]
	v_mfma_f32_16x16x32_bf16 v[32:35], v[178:181], v[194:197], v[32:35]
	v_mfma_f32_16x16x32_bf16 v[20:23], v[170:173], v[202:205], v[20:23]
	v_mfma_f32_16x16x32_bf16 v[16:19], v[178:181], v[202:205], v[16:19]
	v_mfma_f32_16x16x32_bf16 v[4:7], v[170:173], v[226:229], v[4:7]
	v_mfma_f32_16x16x32_bf16 v[0:3], v[178:181], v[226:229], v[0:3]
	s_setprio 0
	s_barrier
	s_add_i32 s73, s73, 2
	s_add_u32 s12, s12, 0x100
	s_addc_u32 s13, s13, 0
	s_add_u32 s54, s54, 0x100
	s_addc_u32 s55, s55, 0
	s_nop 0
